# P8 K-loop: B-operand and As[.][1] LDS-DMA issue moved from the load segments into the MFMA segments, waits recounted
# speedup vs baseline: 1.0110x; 1.0060x over previous
.LBB0_944:
	ds_read_b128 v[20:23], v196
	ds_read_b128 v[166:169], v196 offset:1024
	ds_read_b128 v[14:17], v196 offset:2048
	ds_read_b128 v[162:165], v196 offset:3072
	ds_read_b128 v[8:11], v197
	ds_read_b128 v[158:161], v197 offset:1024
	ds_read_b128 v[2:5], v197 offset:2048
	ds_read_b128 v[154:157], v197 offset:3072
	s_add_u32 s40, s38, 0xfff80080
	s_addc_u32 s41, s39, -1
	s_cmp_eq_u32 s64, 28
	s_cselect_b32 s43, s23, s41
	s_cselect_b32 s42, s60, s40
	s_cselect_b32 s41, s21, s63
	s_cselect_b32 s40, s61, s62
	v_lshl_add_u64 v[238:239], s[38:39], 0, v[178:179]
	ds_read_b128 v[186:189], v198
	ds_read_b128 v[190:193], v198 offset:1024
	ds_read_b128 v[200:203], v198 offset:2048
	ds_read_b128 v[216:219], v198 offset:3072
	ds_read_b128 v[206:209], v198 offset:4096
	ds_read_b128 v[220:223], v198 offset:5120
	ds_read_b128 v[212:215], v198 offset:6144
	ds_read_b128 v[224:227], v198 offset:7168
	v_lshl_add_u64 v[248:249], s[38:39], 0, v[180:181]
	s_waitcnt vmcnt(6)
	s_waitcnt lgkmcnt(0)
	s_barrier
	s_setprio 1
	s_waitcnt lgkmcnt(0)
	v_mov_b32_e32 v24, v166
	v_mov_b32_e32 v25, v167
	s_nop 1
	v_mfma_scale_f32_16x16x128_f8f6f4 v[150:153], v[20:25], v[186:191], v[150:153], v168, v192 op_sel_hi:[0,0,0] cbsz:2 blgp:2
	v_mov_b32_e32 v18, v162
	v_mov_b32_e32 v19, v163
	s_nop 1
	v_mfma_scale_f32_16x16x128_f8f6f4 v[146:149], v[14:19], v[186:191], v[146:149], v164, v192 op_sel_hi:[0,0,0] cbsz:2 blgp:2
	s_add_i32 m0, s37, 0xc000
	s_nop 0
	global_load_lds_dwordx4 v[238:239], off
	v_mov_b32_e32 v204, v216
	v_mov_b32_e32 v205, v217
	s_nop 1
	v_mfma_scale_f32_16x16x128_f8f6f4 v[142:145], v[20:25], v[200:205], v[142:145], v168, v218 op_sel_hi:[0,0,0] cbsz:2 blgp:2
	s_nop 1
	v_mfma_scale_f32_16x16x128_f8f6f4 v[138:141], v[14:19], v[200:205], v[138:141], v164, v218 op_sel_hi:[0,0,0] cbsz:2 blgp:2
	v_mov_b32_e32 v210, v220
	v_mov_b32_e32 v211, v221
	s_nop 1
	v_mfma_scale_f32_16x16x128_f8f6f4 v[134:137], v[20:25], v[206:211], v[134:137], v168, v222 op_sel_hi:[0,0,0] cbsz:2 blgp:2
	s_nop 1
	v_mfma_scale_f32_16x16x128_f8f6f4 v[130:133], v[14:19], v[206:211], v[130:133], v164, v222 op_sel_hi:[0,0,0] cbsz:2 blgp:2
	s_add_i32 m0, s37, 0xe000
	s_nop 0
	global_load_lds_dwordx4 v[248:249], off
	v_mov_b32_e32 v216, v224
	v_mov_b32_e32 v217, v225
	s_nop 1
	v_mfma_scale_f32_16x16x128_f8f6f4 v[126:129], v[20:25], v[212:217], v[126:129], v168, v226 op_sel_hi:[0,0,0] cbsz:2 blgp:2
	s_nop 1
	v_mfma_scale_f32_16x16x128_f8f6f4 v[122:125], v[14:19], v[212:217], v[122:125], v164, v226 op_sel_hi:[0,0,0] cbsz:2 blgp:2
	s_setprio 0
	s_setprio 1
	v_mov_b32_e32 v12, v158
	v_mov_b32_e32 v13, v159
	s_nop 1
	v_mfma_scale_f32_16x16x128_f8f6f4 v[118:121], v[8:13], v[186:191], v[118:121], v160, v192 op_sel_hi:[0,0,0] cbsz:2 blgp:2
	v_mov_b32_e32 v6, v154
	v_mov_b32_e32 v7, v155
	s_nop 1
	v_mfma_scale_f32_16x16x128_f8f6f4 v[114:117], v[2:7], v[186:191], v[114:117], v156, v192 op_sel_hi:[0,0,0] cbsz:2 blgp:2
	s_nop 1
	v_mfma_scale_f32_16x16x128_f8f6f4 v[110:113], v[8:13], v[200:205], v[110:113], v160, v218 op_sel_hi:[0,0,0] cbsz:2 blgp:2
	s_nop 1
	v_mfma_scale_f32_16x16x128_f8f6f4 v[106:109], v[2:7], v[200:205], v[106:109], v156, v218 op_sel_hi:[0,0,0] cbsz:2 blgp:2
	s_nop 1
	v_mfma_scale_f32_16x16x128_f8f6f4 v[102:105], v[8:13], v[206:211], v[102:105], v160, v222 op_sel_hi:[0,0,0] cbsz:2 blgp:2
	s_nop 1
	v_mfma_scale_f32_16x16x128_f8f6f4 v[98:101], v[2:7], v[206:211], v[98:101], v156, v222 op_sel_hi:[0,0,0] cbsz:2 blgp:2
	s_nop 1
	v_mfma_scale_f32_16x16x128_f8f6f4 v[94:97], v[8:13], v[212:217], v[94:97], v160, v226 op_sel_hi:[0,0,0] cbsz:2 blgp:2
	s_nop 1
	v_mfma_scale_f32_16x16x128_f8f6f4 v[90:93], v[2:7], v[212:217], v[90:93], v156, v226 op_sel_hi:[0,0,0] cbsz:2 blgp:2
	s_setprio 0
	s_barrier
	v_lshl_add_u64 v[186:187], s[40:41], 0, v[174:175]
	v_lshl_add_u64 v[190:191], s[42:43], 0, v[176:177]
	s_mov_b32 m0, s37
	ds_read_b128 v[200:203], v198 offset:16384
	ds_read_b128 v[222:225], v198 offset:17408
	ds_read_b128 v[206:209], v198 offset:18432
	ds_read_b128 v[226:229], v198 offset:19456
	ds_read_b128 v[212:215], v198 offset:20480
	ds_read_b128 v[230:233], v198 offset:21504
	ds_read_b128 v[218:221], v198 offset:22528
	ds_read_b128 v[234:237], v198 offset:23552
	global_load_lds_dwordx4 v[190:191], off
	v_lshl_add_u64 v[192:193], s[42:43], 0, v[172:173]
	s_mov_b32 m0, s48
	s_add_u32 s44, s40, 0x80000
	global_load_lds_dwordx4 v[192:193], off
	s_addc_u32 s45, s41, 0
	v_lshl_add_u64 v[188:189], s[40:41], 0, v[170:171]
	v_lshl_add_u64 v[240:241], s[44:45], 0, v[174:175]
	v_lshl_add_u64 v[242:243], s[44:45], 0, v[170:171]
	s_waitcnt vmcnt(4)
	s_waitcnt lgkmcnt(0)
	s_barrier
	s_setprio 1
	s_waitcnt lgkmcnt(0)
	v_mov_b32_e32 v204, v222
	v_mov_b32_e32 v205, v223
	s_nop 1
	v_mfma_scale_f32_16x16x128_f8f6f4 v[86:89], v[20:25], v[200:205], v[86:89], v168, v224 op_sel_hi:[0,0,0] cbsz:2 blgp:2
	s_nop 1
	v_mfma_scale_f32_16x16x128_f8f6f4 v[82:85], v[14:19], v[200:205], v[82:85], v164, v224 op_sel_hi:[0,0,0] cbsz:2 blgp:2
	s_add_i32 m0, s37, 0x10000
	s_nop 0
	global_load_lds_dwordx4 v[186:187], off
	v_mov_b32_e32 v210, v226
	v_mov_b32_e32 v211, v227
	s_nop 1
	v_mfma_scale_f32_16x16x128_f8f6f4 v[78:81], v[20:25], v[206:211], v[78:81], v168, v228 op_sel_hi:[0,0,0] cbsz:2 blgp:2
	s_nop 1
	v_mfma_scale_f32_16x16x128_f8f6f4 v[74:77], v[14:19], v[206:211], v[74:77], v164, v228 op_sel_hi:[0,0,0] cbsz:2 blgp:2
	v_mov_b32_e32 v216, v230
	v_mov_b32_e32 v217, v231
	s_nop 1
	v_mfma_scale_f32_16x16x128_f8f6f4 v[70:73], v[20:25], v[212:217], v[70:73], v168, v232 op_sel_hi:[0,0,0] cbsz:2 blgp:2
	s_add_i32 m0, s37, 0x12000
	s_nop 0
	global_load_lds_dwordx4 v[188:189], off
	s_nop 1
	v_mfma_scale_f32_16x16x128_f8f6f4 v[66:69], v[14:19], v[212:217], v[66:69], v164, v232 op_sel_hi:[0,0,0] cbsz:2 blgp:2
	v_mov_b32_e32 v222, v234
	v_mov_b32_e32 v223, v235
	s_nop 1
	v_mfma_scale_f32_16x16x128_f8f6f4 v[62:65], v[20:25], v[218:223], v[62:65], v168, v236 op_sel_hi:[0,0,0] cbsz:2 blgp:2
	s_nop 1
	v_mfma_scale_f32_16x16x128_f8f6f4 v[58:61], v[14:19], v[218:223], v[58:61], v164, v236 op_sel_hi:[0,0,0] cbsz:2 blgp:2
	s_add_i32 m0, s37, 0x14000
	s_nop 0
	global_load_lds_dwordx4 v[240:241], off
	s_setprio 0
	s_setprio 1
	s_nop 1
	v_mfma_scale_f32_16x16x128_f8f6f4 v[54:57], v[8:13], v[200:205], v[54:57], v160, v224 op_sel_hi:[0,0,0] cbsz:2 blgp:2
	s_nop 1
	v_mfma_scale_f32_16x16x128_f8f6f4 v[50:53], v[2:7], v[200:205], v[50:53], v156, v224 op_sel_hi:[0,0,0] cbsz:2 blgp:2
	s_nop 1
	v_mfma_scale_f32_16x16x128_f8f6f4 v[46:49], v[8:13], v[206:211], v[46:49], v160, v228 op_sel_hi:[0,0,0] cbsz:2 blgp:2
	s_add_i32 m0, s37, 0x16000
	s_nop 0
	global_load_lds_dwordx4 v[242:243], off
	s_nop 1
	v_mfma_scale_f32_16x16x128_f8f6f4 v[42:45], v[2:7], v[206:211], v[42:45], v156, v228 op_sel_hi:[0,0,0] cbsz:2 blgp:2
	s_nop 1
	v_mfma_scale_f32_16x16x128_f8f6f4 v[38:41], v[8:13], v[212:217], v[38:41], v160, v232 op_sel_hi:[0,0,0] cbsz:2 blgp:2
	s_nop 1
	v_mfma_scale_f32_16x16x128_f8f6f4 v[34:37], v[2:7], v[212:217], v[34:37], v156, v232 op_sel_hi:[0,0,0] cbsz:2 blgp:2
	s_nop 1
	v_mfma_scale_f32_16x16x128_f8f6f4 v[30:33], v[8:13], v[218:223], v[30:33], v160, v236 op_sel_hi:[0,0,0] cbsz:2 blgp:2
	s_nop 1
	v_mfma_scale_f32_16x16x128_f8f6f4 v[26:29], v[2:7], v[218:223], v[26:29], v156, v236 op_sel_hi:[0,0,0] cbsz:2 blgp:2
	s_setprio 0
	s_barrier
	s_add_i32 s44, 0, 0x18000
	s_add_i32 s45, 0, 0x1c000
	v_add_u32_e32 v2, s44, v1
	v_add_u32_e32 v6, s45, v1
	ds_read_b128 v[20:23], v2
	ds_read_b128 v[166:169], v2 offset:1024
	ds_read_b128 v[14:17], v2 offset:2048
	ds_read_b128 v[162:165], v2 offset:3072
	ds_read_b128 v[8:11], v6
	ds_read_b128 v[154:157], v6 offset:1024
	ds_read_b128 v[2:5], v6 offset:2048
	ds_read_b128 v[158:161], v6 offset:3072
	s_add_u32 s42, s42, 0x80000
	s_addc_u32 s43, s43, 0
	v_lshl_add_u64 v[244:245], s[42:43], 0, v[176:177]
	ds_read_b128 v[200:203], v198 offset:32768
	ds_read_b128 v[222:225], v198 offset:33792
	ds_read_b128 v[206:209], v198 offset:34816
	ds_read_b128 v[226:229], v198 offset:35840
	ds_read_b128 v[212:215], v198 offset:36864
	ds_read_b128 v[230:233], v198 offset:37888
	ds_read_b128 v[218:221], v198 offset:38912
	ds_read_b128 v[234:237], v198 offset:39936
	v_lshl_add_u64 v[246:247], s[42:43], 0, v[172:173]
	s_waitcnt vmcnt(6)
	s_waitcnt lgkmcnt(0)
	s_barrier
	s_setprio 1
	s_waitcnt lgkmcnt(0)
	v_mov_b32_e32 v204, v222
	v_mov_b32_e32 v205, v223
	v_mov_b32_e32 v24, v166
	v_mov_b32_e32 v25, v167
	s_nop 1
	v_mfma_scale_f32_16x16x128_f8f6f4 v[150:153], v[20:25], v[200:205], v[150:153], v168, v224 op_sel_hi:[0,0,0] cbsz:2 blgp:2
	v_mov_b32_e32 v18, v162
	v_mov_b32_e32 v19, v163
	s_nop 1
	v_mfma_scale_f32_16x16x128_f8f6f4 v[146:149], v[14:19], v[200:205], v[146:149], v164, v224 op_sel_hi:[0,0,0] cbsz:2 blgp:2
	s_mov_b32 m0, s49
	s_nop 0
	global_load_lds_dwordx4 v[244:245], off
	v_mov_b32_e32 v210, v226
	v_mov_b32_e32 v211, v227
	s_nop 1
	v_mfma_scale_f32_16x16x128_f8f6f4 v[142:145], v[20:25], v[206:211], v[142:145], v168, v228 op_sel_hi:[0,0,0] cbsz:2 blgp:2
	s_nop 1
	v_mfma_scale_f32_16x16x128_f8f6f4 v[138:141], v[14:19], v[206:211], v[138:141], v164, v228 op_sel_hi:[0,0,0] cbsz:2 blgp:2
	v_mov_b32_e32 v216, v230
	v_mov_b32_e32 v217, v231
	s_nop 1
	v_mfma_scale_f32_16x16x128_f8f6f4 v[134:137], v[20:25], v[212:217], v[134:137], v168, v232 op_sel_hi:[0,0,0] cbsz:2 blgp:2
	s_nop 1
	v_mfma_scale_f32_16x16x128_f8f6f4 v[130:133], v[14:19], v[212:217], v[130:133], v164, v232 op_sel_hi:[0,0,0] cbsz:2 blgp:2
	s_mov_b32 m0, s50
	s_nop 0
	global_load_lds_dwordx4 v[246:247], off
	v_mov_b32_e32 v222, v234
	v_mov_b32_e32 v223, v235
	s_nop 1
	v_mfma_scale_f32_16x16x128_f8f6f4 v[126:129], v[20:25], v[218:223], v[126:129], v168, v236 op_sel_hi:[0,0,0] cbsz:2 blgp:2
	s_nop 1
	v_mfma_scale_f32_16x16x128_f8f6f4 v[122:125], v[14:19], v[218:223], v[122:125], v164, v236 op_sel_hi:[0,0,0] cbsz:2 blgp:2
	s_setprio 0
	s_setprio 1
	v_mov_b32_e32 v12, v154
	v_mov_b32_e32 v13, v155
	s_nop 1
	v_mfma_scale_f32_16x16x128_f8f6f4 v[118:121], v[8:13], v[200:205], v[118:121], v156, v224 op_sel_hi:[0,0,0] cbsz:2 blgp:2
	v_mov_b32_e32 v6, v158
	v_mov_b32_e32 v7, v159
	s_nop 1
	v_mfma_scale_f32_16x16x128_f8f6f4 v[114:117], v[2:7], v[200:205], v[114:117], v160, v224 op_sel_hi:[0,0,0] cbsz:2 blgp:2
	s_nop 1
	v_mfma_scale_f32_16x16x128_f8f6f4 v[110:113], v[8:13], v[206:211], v[110:113], v156, v228 op_sel_hi:[0,0,0] cbsz:2 blgp:2
	s_nop 1
	v_mfma_scale_f32_16x16x128_f8f6f4 v[106:109], v[2:7], v[206:211], v[106:109], v160, v228 op_sel_hi:[0,0,0] cbsz:2 blgp:2
	s_nop 1
	v_mfma_scale_f32_16x16x128_f8f6f4 v[102:105], v[8:13], v[212:217], v[102:105], v156, v232 op_sel_hi:[0,0,0] cbsz:2 blgp:2
	s_nop 1
	v_mfma_scale_f32_16x16x128_f8f6f4 v[98:101], v[2:7], v[212:217], v[98:101], v160, v232 op_sel_hi:[0,0,0] cbsz:2 blgp:2
	s_nop 1
	v_mfma_scale_f32_16x16x128_f8f6f4 v[94:97], v[8:13], v[218:223], v[94:97], v156, v236 op_sel_hi:[0,0,0] cbsz:2 blgp:2
	s_nop 1
	v_mfma_scale_f32_16x16x128_f8f6f4 v[90:93], v[2:7], v[218:223], v[90:93], v160, v236 op_sel_hi:[0,0,0] cbsz:2 blgp:2
	s_setprio 0
	s_barrier
	v_lshl_add_u64 v[154:155], v[190:191], 0, s[12:13]
	s_mov_b32 m0, s53
	ds_read_b128 v[200:203], v198 offset:49152
	ds_read_b128 v[222:225], v198 offset:50176
	ds_read_b128 v[206:209], v198 offset:51200
	ds_read_b128 v[226:229], v198 offset:52224
	ds_read_b128 v[212:215], v198 offset:53248
	ds_read_b128 v[230:233], v198 offset:54272
	ds_read_b128 v[218:221], v198 offset:55296
	ds_read_b128 v[234:237], v198 offset:56320
	global_load_lds_dwordx4 v[154:155], off
	v_lshl_add_u64 v[154:155], v[192:193], 0, s[12:13]
	s_mov_b32 m0, s54
	s_add_u32 s40, s40, 0x80080
	global_load_lds_dwordx4 v[154:155], off
	s_addc_u32 s41, s41, 0
	v_lshl_add_u64 v[238:239], v[186:187], 0, s[12:13]
	v_lshl_add_u64 v[248:249], v[188:189], 0, s[12:13]
	v_lshl_add_u64 v[240:241], s[40:41], 0, v[174:175]
	v_lshl_add_u64 v[242:243], s[40:41], 0, v[170:171]
	s_waitcnt vmcnt(4)
	s_waitcnt lgkmcnt(0)
	s_barrier
	s_setprio 1
	s_waitcnt lgkmcnt(0)
	v_mov_b32_e32 v204, v222
	v_mov_b32_e32 v205, v223
	s_nop 1
	v_mfma_scale_f32_16x16x128_f8f6f4 v[86:89], v[20:25], v[200:205], v[86:89], v168, v224 op_sel_hi:[0,0,0] cbsz:2 blgp:2
	s_nop 1
	v_mfma_scale_f32_16x16x128_f8f6f4 v[82:85], v[14:19], v[200:205], v[82:85], v164, v224 op_sel_hi:[0,0,0] cbsz:2 blgp:2
	s_add_i32 m0, s37, 0x18000
	s_nop 0
	global_load_lds_dwordx4 v[238:239], off
	v_mov_b32_e32 v210, v226
	v_mov_b32_e32 v211, v227
	s_nop 1
	v_mfma_scale_f32_16x16x128_f8f6f4 v[78:81], v[20:25], v[206:211], v[78:81], v168, v228 op_sel_hi:[0,0,0] cbsz:2 blgp:2
	s_nop 1
	v_mfma_scale_f32_16x16x128_f8f6f4 v[74:77], v[14:19], v[206:211], v[74:77], v164, v228 op_sel_hi:[0,0,0] cbsz:2 blgp:2
	v_mov_b32_e32 v216, v230
	v_mov_b32_e32 v217, v231
	s_nop 1
	v_mfma_scale_f32_16x16x128_f8f6f4 v[70:73], v[20:25], v[212:217], v[70:73], v168, v232 op_sel_hi:[0,0,0] cbsz:2 blgp:2
	s_add_i32 m0, s37, 0x1a000
	s_nop 0
	global_load_lds_dwordx4 v[248:249], off
	s_nop 1
	v_mfma_scale_f32_16x16x128_f8f6f4 v[66:69], v[14:19], v[212:217], v[66:69], v164, v232 op_sel_hi:[0,0,0] cbsz:2 blgp:2
	v_mov_b32_e32 v222, v234
	v_mov_b32_e32 v223, v235
	s_nop 1
	v_mfma_scale_f32_16x16x128_f8f6f4 v[62:65], v[20:25], v[218:223], v[62:65], v168, v236 op_sel_hi:[0,0,0] cbsz:2 blgp:2
	s_nop 1
	v_mfma_scale_f32_16x16x128_f8f6f4 v[58:61], v[14:19], v[218:223], v[58:61], v164, v236 op_sel_hi:[0,0,0] cbsz:2 blgp:2
	s_add_i32 m0, s37, 0x1c000
	s_nop 0
	global_load_lds_dwordx4 v[240:241], off
	s_setprio 0
	s_setprio 1
	s_nop 1
	v_mfma_scale_f32_16x16x128_f8f6f4 v[54:57], v[8:13], v[200:205], v[54:57], v156, v224 op_sel_hi:[0,0,0] cbsz:2 blgp:2
	s_nop 1
	v_mfma_scale_f32_16x16x128_f8f6f4 v[50:53], v[2:7], v[200:205], v[50:53], v160, v224 op_sel_hi:[0,0,0] cbsz:2 blgp:2
	s_nop 1
	v_mfma_scale_f32_16x16x128_f8f6f4 v[46:49], v[8:13], v[206:211], v[46:49], v156, v228 op_sel_hi:[0,0,0] cbsz:2 blgp:2
	s_add_i32 m0, s37, 0x1e000
	s_nop 0
	global_load_lds_dwordx4 v[242:243], off
	s_nop 1
	v_mfma_scale_f32_16x16x128_f8f6f4 v[42:45], v[2:7], v[206:211], v[42:45], v160, v228 op_sel_hi:[0,0,0] cbsz:2 blgp:2
	s_nop 1
	v_mfma_scale_f32_16x16x128_f8f6f4 v[38:41], v[8:13], v[212:217], v[38:41], v156, v232 op_sel_hi:[0,0,0] cbsz:2 blgp:2
	s_nop 1
	v_mfma_scale_f32_16x16x128_f8f6f4 v[34:37], v[2:7], v[212:217], v[34:37], v160, v232 op_sel_hi:[0,0,0] cbsz:2 blgp:2
	s_nop 1
	v_mfma_scale_f32_16x16x128_f8f6f4 v[30:33], v[8:13], v[218:223], v[30:33], v156, v236 op_sel_hi:[0,0,0] cbsz:2 blgp:2
	s_nop 1
	v_mfma_scale_f32_16x16x128_f8f6f4 v[26:29], v[2:7], v[218:223], v[26:29], v160, v236 op_sel_hi:[0,0,0] cbsz:2 blgp:2
	s_setprio 0
	s_barrier
	s_add_i32 s64, s64, 2
	s_add_u32 s38, s38, 0x100
	s_addc_u32 s39, s39, 0
	s_add_u32 s62, s62, 0x100
	s_addc_u32 s63, s63, 0
	s_cmp_lt_u32 s64, 30
	s_cbranch_scc1 .LBB0_944
	s_nop 15
	s_nop 15
	s_andn2_b64 vcc, exec, s[14:15]
	s_cbranch_vccnz .LBB0_947
	s_barrier
